# speedup vs baseline: 1.0094x; 1.0029x over previous
; #define QK_FENCE() __builtin_amdgcn_sched_barrier(0x406)
; DI void finishSM(f32x16& p0, f32x16& p1, float alpha, float& l_reg, bf16x8& pa0, bf16x8& pa1, bf16x8& pa2, bf16x8& pa3) {
; #pragma unroll
;   for (int r = 0; r < 16; ++r) p1[r] = __builtin_amdgcn_exp2f(p1[r]);
;   float ps = 0;
; #pragma unroll
;   for (int r = 0; r < 16; ++r) ps += p0[r];
; #pragma unroll
;   for (int r = 0; r < 16; ++r) ps += p1[r];
;   { auto rr = __builtin_amdgcn_permlane32_swap(__float_as_uint(ps), __float_as_uint(ps), false, false);
;     ps = __uint_as_float(rr[0]) + __uint_as_float(rr[1]); }
;   l_reg = l_reg * alpha + ps;
;     ...
;   PK4(p0, 0, pa0); PK4(p0, 8, pa1); PK4(p1, 0, pa2); PK4(p1, 8, pa3);
; DI void qkt12(f32x16& p0, f32x16& p1, const char* Kt, const char* Rt, const int* ko, const int* ro, const bf16x8* qr) {
;   { const f32x16 z = {0.f, 0.f, 0.f, 0.f, 0.f, 0.f, 0.f, 0.f, 0.f, 0.f, 0.f, 0.f, 0.f, 0.f, 0.f, 0.f}; p0 = z; p1 = z; }
;   const char* kp[4] = {Kt + ko[0], Kt + ko[1], Kt + ko[2], Kt + ko[3]};
;   const char* rp[4] = {Rt + ro[0], Rt + ro[1], Rt + ro[2], Rt + ro[3]};
;   bf16x8 ka[2], kb[2];
;   ka[0] = *reinterpret_cast<const bf16x8*>(kp[0]); kb[0] = *reinterpret_cast<const bf16x8*>(kp[0] + 8192);
; #pragma unroll
;   for (int d0 = 0; d0 < 12; ++d0) {
;     if (d0 + 1 < 12) { const int d1 = d0 + 1;
;       if (d1 < 8) { ka[d1 & 1] = *reinterpret_cast<const bf16x8*>(kp[d1 & 3] + (d1 >> 2) * 128); kb[d1 & 1] = *reinterpret_cast<const bf16x8*>(kp[d1 & 3] + (d1 >> 2) * 128 + 8192); }
;       else { ka[d1 & 1] = *reinterpret_cast<const bf16x8*>(rp[d1 - 8]); kb[d1 & 1] = *reinterpret_cast<const bf16x8*>(rp[d1 - 8] + 4096); } }
;     QK_FENCE();
;     p0 = __builtin_amdgcn_mfma_f32_32x32x16_bf16(ka[d0 & 1], qr[d0], p0, 0, 0, 0);
;     p1 = __builtin_amdgcn_mfma_f32_32x32x16_bf16(kb[d0 & 1], qr[d0], p1, 0, 0, 0);
;     QK_FENCE();
;   }
.LBB0_122:
	v_sub_co_u32_e64 v64, s[6:7], s61, 1
	s_and_b64 s[6:7], s[6:7], exec
	v_readfirstlane_b32 s2, v64
	s_cselect_b32 s13, 2, s2
	s_mul_i32 s42, s61, 0xa000
	s_add_i32 s45, s42, 16
	v_add_u32_e32 v177, s45, v176
	ds_read_b128 v[64:67], v177 offset:16384
	v_add_u32_e32 v220, s45, v179
	ds_read_b128 v[68:71], v177 offset:24576
	ds_read_b128 v[188:191], v220 offset:16384
	ds_read_b128 v[208:211], v220 offset:24576
	v_add_u32_e32 v221, s45, v180
	v_add_u32_e32 v222, s45, v181
	v_exp_f32_e32 v200, v200
	v_exp_f32_e32 v202, v202
	v_exp_f32_e32 v201, v201
	v_exp_f32_e32 v204, v204
	v_exp_f32_e32 v203, v203
	v_exp_f32_e32 v206, v206
	v_exp_f32_e32 v205, v205
	v_exp_f32_e32 v207, v207
	v_exp_f32_e32 v192, v192
	v_exp_f32_e32 v194, v194
	v_exp_f32_e32 v193, v193
	v_exp_f32_e32 v196, v196
	v_exp_f32_e32 v195, v195
	v_exp_f32_e32 v198, v198
	v_exp_f32_e32 v197, v197
	v_exp_f32_e32 v199, v199
	v_exp_f32_e32 v166, v166
	s_waitcnt lgkmcnt(3)
	v_mfma_f32_32x32x16_bf16 v[80:95], v[64:67], v[134:137], 0
	v_exp_f32_e32 v167, v167
	v_exp_f32_e32 v163, v163
	v_exp_f32_e32 v168, v168
	v_mfma_f32_32x32x16_bf16 v[64:79], v[68:71], v[134:137], 0
	ds_read_b128 v[212:215], v221 offset:16384
	ds_read_b128 v[216:219], v221 offset:24576
	v_exp_f32_e32 v169, v169
	v_exp_f32_e32 v235, v162
	v_exp_f32_e32 v237, v164
	s_waitcnt lgkmcnt(2)
	v_mfma_f32_32x32x16_bf16 v[64:79], v[208:211], v[130:133], v[64:79]
	s_add_i32 s2, s42, 0xa000
	s_cmp_lg_u32 s61, 2
	s_cselect_b32 s2, s2, 0
	v_add_u32_e32 v240, s2, v178
	s_add_u32 s0, s82, 0x1bbc0100
	s_addc_u32 s1, s83, 0
	v_lshl_add_u64 v[238:239], v[150:151], 0, s[0:1]
	v_readfirstlane_b32 s2, v240
	s_mov_b32 m0, s2
	v_exp_f32_e32 v241, v165
	global_load_lds_dwordx4 v[238:239], off
	v_mfma_f32_32x32x16_bf16 v[80:95], v[188:191], v[130:133], v[80:95]
	ds_read_b128 v[188:191], v222 offset:16384
	ds_read_b128 v[208:211], v222 offset:24576
	v_exp_f32_e32 v243, v158
	v_exp_f32_e32 v244, v159
	v_exp_f32_e32 v245, v154
	s_waitcnt lgkmcnt(2)
	v_mfma_f32_32x32x16_bf16 v[64:79], v[216:219], v[126:129], v[64:79]
	v_add_f32_e32 v154, 0, v200
	v_add_f32_e32 v154, v202, v154
	v_add_f32_e32 v154, v201, v154
	v_add_f32_e32 v154, v204, v154
	v_add_f32_e32 v154, v203, v154
	v_add_f32_e32 v154, v206, v154
	v_mfma_f32_32x32x16_bf16 v[80:95], v[212:215], v[126:129], v[80:95]
	ds_read_b128 v[212:215], v177 offset:16512
	ds_read_b128 v[216:219], v177 offset:24704
	v_add_u32_e32 v177, s45, v182
	v_add_f32_e32 v154, v205, v154
	v_add_f32_e32 v154, v207, v154
	v_add_f32_e32 v154, v192, v154
	v_add_f32_e32 v154, v194, v154
	v_add_f32_e32 v154, v193, v154
	s_waitcnt lgkmcnt(2)
	v_mfma_f32_32x32x16_bf16 v[64:79], v[208:211], v[114:117], v[64:79]
	v_add_u32_e32 v242, 0x2000, v240
	s_add_u32 s0, s82, 0x1bbe0100
	s_addc_u32 s1, s83, 0
	v_lshl_add_u64 v[238:239], v[150:151], 0, s[0:1]
	v_readfirstlane_b32 s2, v242
	s_mov_b32 m0, s2
	v_add_f32_e32 v154, v196, v154
	global_load_lds_dwordx4 v[238:239], off
	v_add_f32_e32 v154, v195, v154
	v_add_f32_e32 v154, v198, v154
	v_mfma_f32_32x32x16_bf16 v[80:95], v[188:191], v[114:117], v[80:95]
	ds_read_b128 v[188:191], v220 offset:16512
	ds_read_b128 v[208:211], v220 offset:24704
	v_add_f32_e32 v154, v197, v154
	v_add_f32_e32 v154, v199, v154
	v_exp_f32_e32 v246, v160
	v_add_f32_e32 v154, v166, v154
	s_waitcnt lgkmcnt(2)
	v_mfma_f32_32x32x16_bf16 v[64:79], v[216:219], v[110:113], v[64:79]
	v_exp_f32_e32 v248, v161
	v_add_f32_e32 v154, v167, v154
	v_exp_f32_e32 v249, v156
	v_add_f32_e32 v154, v235, v154
	v_mfma_f32_32x32x16_bf16 v[80:95], v[212:215], v[110:113], v[80:95]
	ds_read_b128 v[212:215], v221 offset:16512
	ds_read_b128 v[216:219], v221 offset:24704
	v_exp_f32_e32 v250, v157
	v_add_f32_e32 v154, v163, v154
	v_add_f32_e32 v154, v246, v154
	v_exp_f32_e32 v251, v155
	s_waitcnt lgkmcnt(2)
	v_mfma_f32_32x32x16_bf16 v[64:79], v[208:211], v[106:109], v[64:79]
	v_add_u32_e32 v242, 0x4000, v240
	s_add_u32 s0, s82, 0x1bbc0000
	s_addc_u32 s1, s83, 0
	v_lshl_add_u64 v[238:239], v[152:153], 0, s[0:1]
	v_readfirstlane_b32 s2, v242
	s_mov_b32 m0, s2
	v_add_f32_e32 v154, v248, v154
	global_load_lds_dwordx4 v[238:239], off
	v_add_f32_e32 v154, v249, v154
	v_add_f32_e32 v154, v250, v154
	v_mfma_f32_32x32x16_bf16 v[80:95], v[188:191], v[106:109], v[80:95]
	ds_read_b128 v[188:191], v222 offset:16512
	ds_read_b128 v[208:211], v222 offset:24704
	v_add_f32_e32 v154, v245, v154
	v_add_f32_e32 v154, v251, v154
	v_add_f32_e32 v154, v168, v154
	v_add_f32_e32 v154, v169, v154
	v_add_f32_e32 v154, v237, v154
	v_add_f32_e32 v154, v241, v154
	s_waitcnt lgkmcnt(2)
	v_mfma_f32_32x32x16_bf16 v[64:79], v[216:219], v[102:105], v[64:79]
	v_add_f32_e32 v154, v243, v154
	v_cvt_pk_bf16_f32 v155, v201, v204
	v_cvt_pk_bf16_f32 v156, v203, v206
	v_cvt_pk_bf16_f32 v157, v205, v207
	v_cvt_pk_bf16_f32 v158, v192, v194
	v_cvt_pk_bf16_f32 v159, v193, v196
	v_mfma_f32_32x32x16_bf16 v[80:95], v[212:215], v[102:105], v[80:95]
	ds_read_b128 v[212:215], v177 offset:32768
	ds_read_b128 v[216:219], v177 offset:36864
	v_add_u32_e32 v177, s45, v183
	v_cvt_pk_bf16_f32 v160, v195, v198
	v_cvt_pk_bf16_f32 v161, v197, v199
	v_permlane32_swap_b32_e32 v155, v157
	v_permlane32_swap_b32_e32 v158, v160
	v_permlane32_swap_b32_e32 v159, v161
	s_waitcnt lgkmcnt(2)
	v_mfma_f32_32x32x16_bf16 v[64:79], v[208:211], v[98:101], v[64:79]
	v_add_u32_e32 v242, 0x6000, v240
	s_add_u32 s0, s82, 0x1bbe0000
	s_addc_u32 s1, s83, 0
	v_lshl_add_u64 v[238:239], v[152:153], 0, s[0:1]
	v_readfirstlane_b32 s2, v242
	s_mov_b32 m0, s2
	v_cvt_pk_bf16_f32 v162, v166, v167
	global_load_lds_dwordx4 v[238:239], off
	v_cvt_pk_bf16_f32 v163, v235, v163
	v_cvt_pk_bf16_f32 v164, v246, v248
	v_mfma_f32_32x32x16_bf16 v[80:95], v[188:191], v[98:101], v[80:95]
	ds_read_b128 v[188:191], v177 offset:32768
	ds_read_b128 v[208:211], v177 offset:36864
	v_add_u32_e32 v177, s45, v184
	v_cvt_pk_bf16_f32 v165, v249, v250
	v_cvt_pk_bf16_f32 v166, v245, v251
	v_cvt_pk_bf16_f32 v167, v168, v169
	v_cvt_pk_bf16_f32 v168, v237, v241
	v_cvt_pk_bf16_f32 v169, v243, v244
	s_waitcnt lgkmcnt(2)
; #define SBAR() __builtin_amdgcn_sched_barrier(0)
; template <int OFF> DI s16x4 tr_read(int vb) { s16x4 r; asm volatile("ds_read_b64_tr_b16 %0, %1 offset:%2" : "=&v"(r) : "v"(vb), "i"(OFF) : "memory"); return r; }
; DI void partialSM(f32x16& p0, f32x16& p1, float& m_reg, float& mn, float& alpha) {
;   constexpr float C = ATT_SCALE * 1.4426950408889634f;
;   float pmax = p0[0];
; #pragma unroll
;   for (int r = 1; r < 16; ++r) pmax = fmaxf(pmax, p0[r]);
; #pragma unroll
;   for (int r = 0; r < 16; ++r) pmax = fmaxf(pmax, p1[r]);
;   { auto rr = __builtin_amdgcn_permlane32_swap(__float_as_uint(pmax), __float_as_uint(pmax), false, false);
;     pmax = fmaxf(__uint_as_float(rr[0]), __uint_as_float(rr[1])); }
;   if (__builtin_expect(__all(pmax - m_reg <= ATT_THR / ATT_SCALE), 1)) { mn = m_reg; alpha = 1.f; }
; template <int D0> DI void pv_one(f32x16& od, int vb, bf16x8 pa0, bf16x8 pa1, bf16x8 pa2, bf16x8 pa3) {
;   const s16x4 l0 = tr_read<v_rd_off(D0, 0, 0)>(vb), h0 = tr_read<v_rd_off(D0, 0, 1)>(vb), l1 = tr_read<v_rd_off(D0, 1, 0)>(vb), h1 = tr_read<v_rd_off(D0, 1, 1)>(vb);
;   const s16x4 l2 = tr_read<v_rd_off(D0, 2, 0)>(vb), h2 = tr_read<v_rd_off(D0, 2, 1)>(vb), l3 = tr_read<v_rd_off(D0, 3, 0)>(vb), h3 = tr_read<v_rd_off(D0, 3, 1)>(vb);
;   asm volatile("s_waitcnt lgkmcnt(0)" ::: "memory"); SBAR();
;     ...
;   od = __builtin_amdgcn_mfma_f32_32x32x16_bf16(pa0, PK(l0, h0), od, 0, 0, 0);
;   od = __builtin_amdgcn_mfma_f32_32x32x16_bf16(pa1, PK(l1, h1), od, 0, 0, 0);
;   od = __builtin_amdgcn_mfma_f32_32x32x16_bf16(pa2, PK(l2, h2), od, 0, 0, 0);
;   od = __builtin_amdgcn_mfma_f32_32x32x16_bf16(pa3, PK(l3, h3), od, 0, 0, 0);
;     ...
; }
; DI void pv_d0(f32x16* o, int vb, bf16x8 pa0, bf16x8 pa1, bf16x8 pa2, bf16x8 pa3) {
;   pv_one<0>(o[0], vb, pa0, pa1, pa2, pa3); pv_one<1>(o[1], vb, pa0, pa1, pa2, pa3); pv_one<2>(o[2], vb, pa0, pa1, pa2, pa3); pv_one<3>(o[3], vb, pa0, pa1, pa2, pa3);
	v_mfma_f32_32x32x16_bf16 v[64:79], v[216:219], v[122:125], v[64:79]
	v_permlane32_swap_b32_e32 v162, v164
	v_permlane32_swap_b32_e32 v163, v165
	v_permlane32_swap_b32_e32 v166, v168
	v_permlane32_swap_b32_e32 v167, v169
	v_mfma_f32_32x32x16_bf16 v[80:95], v[212:215], v[122:125], v[80:95]
	ds_read_b128 v[212:215], v177 offset:32768
	ds_read_b128 v[216:219], v177 offset:36864
	v_add_u32_e32 v177, s45, v185
	s_waitcnt lgkmcnt(2)
	v_mfma_f32_32x32x16_bf16 v[64:79], v[208:211], v[142:145], v[64:79]
	v_add_u32_e32 v242, 0x8000, v240
	s_add_u32 s0, s82, 0x1fb44000
	s_addc_u32 s1, s83, 0
	v_lshl_add_u64 v[238:239], v[148:149], 0, s[0:1]
	v_readfirstlane_b32 s2, v242
	s_mov_b32 m0, s2
	s_nop 0
	global_load_lds_dwordx4 v[238:239], off
	s_movk_i32 s0, 0x410
	s_movk_i32 s1, 0x1800
	v_mfma_f32_32x32x16_bf16 v[80:95], v[188:191], v[142:145], v[80:95]
	ds_read_b128 v[188:191], v177 offset:32768
	ds_read_b128 v[208:211], v177 offset:36864
	s_waitcnt lgkmcnt(2)
	v_mfma_f32_32x32x16_bf16 v[64:79], v[216:219], v[118:121], v[64:79]
	v_mfma_f32_32x32x16_bf16 v[80:95], v[212:215], v[118:121], v[80:95]
	s_waitcnt lgkmcnt(0)
	v_mfma_f32_32x32x16_bf16 v[64:79], v[208:211], v[138:141], v[64:79]
	v_mfma_f32_32x32x16_bf16 v[80:95], v[188:191], v[138:141], v[80:95]
	s_mul_i32 s44, s13, 0xa000
	v_add_u32_e32 v177, s44, v174
	ds_read_b64_tr_b16 v[190:191], v177 offset:0
	ds_read_b64_tr_b16 v[192:193], v177 offset:0x800
	ds_read_b64_tr_b16 v[194:195], v177 offset:0x1000
	ds_read_b64_tr_b16 v[196:197], v177 offset:0x1800
	ds_read_b64_tr_b16 v[198:199], v177 offset:0x2000
	v_add_f32_e32 v188, v244, v154
	v_mov_b32_e32 v189, v188
	v_cvt_pk_bf16_f32 v154, v200, v202
	ds_read_b64_tr_b16 v[200:201], v177 offset:0x2800
	ds_read_b64_tr_b16 v[202:203], v177 offset:0x3000
	ds_read_b64_tr_b16 v[204:205], v177 offset:0x3800
	v_permlane32_swap_b32_e32 v188, v189
	v_permlane32_swap_b32_e32 v154, v156
	s_waitcnt lgkmcnt(6)
	v_max_f32_e32 v235, v81, v81
	v_mfma_f32_32x32x16_bf16 v[0:15], v[154:157], v[190:193], v[0:15]
	ds_read_b64_tr_b16 v[190:191], v177 offset:0x200
	ds_read_b64_tr_b16 v[192:193], v177 offset:0xa00
	v_max_f32_e32 v237, v80, v80
	v_max_f32_e32 v235, v237, v235
	v_max3_f32 v235, v235, v82, v83
	v_max3_f32 v235, v235, v84, v85
	v_max3_f32 v235, v235, v86, v87
	v_max3_f32 v235, v235, v88, v89
	s_waitcnt lgkmcnt(6)
	v_mfma_f32_32x32x16_bf16 v[0:15], v[158:161], v[194:197], v[0:15]
	ds_read_b64_tr_b16 v[194:195], v177 offset:0x1200
	ds_read_b64_tr_b16 v[196:197], v177 offset:0x1a00
	v_max3_f32 v235, v235, v90, v91
	v_max3_f32 v235, v235, v92, v93
	v_max3_f32 v235, v235, v94, v95
	v_max3_f32 v235, v235, v64, v65
	v_max3_f32 v235, v235, v66, v67
	v_max3_f32 v235, v235, v68, v69
	s_waitcnt lgkmcnt(6)
	v_mfma_f32_32x32x16_bf16 v[0:15], v[162:165], v[198:201], v[0:15]
	ds_read_b64_tr_b16 v[198:199], v177 offset:0x2200
	ds_read_b64_tr_b16 v[200:201], v177 offset:0x2a00
	v_max3_f32 v235, v235, v70, v71
	v_max3_f32 v235, v235, v72, v73
	v_max3_f32 v235, v235, v74, v75
	v_max3_f32 v235, v235, v76, v77
	v_max3_f32 v235, v235, v78, v79
	v_mov_b32_e32 v237, v235
	s_waitcnt lgkmcnt(6)
	v_mfma_f32_32x32x16_bf16 v[0:15], v[166:169], v[202:205], v[0:15]
	ds_read_b64_tr_b16 v[202:203], v177 offset:0x3200
	ds_read_b64_tr_b16 v[204:205], v177 offset:0x3a00
	v_permlane32_swap_b32_e32 v235, v237
	v_max_f32_e32 v237, v237, v237
	v_max_f32_e32 v235, v235, v235
	s_waitcnt lgkmcnt(6)
	v_mfma_f32_32x32x16_bf16 v[48:63], v[154:157], v[190:193], v[48:63]
	ds_read_b64_tr_b16 v[190:191], v177 offset:0x400
	ds_read_b64_tr_b16 v[192:193], v177 offset:0xc00
	s_waitcnt lgkmcnt(6)
	v_mfma_f32_32x32x16_bf16 v[48:63], v[158:161], v[194:197], v[48:63]
	ds_read_b64_tr_b16 v[194:195], v177 offset:0x1400
	ds_read_b64_tr_b16 v[196:197], v177 offset:0x1c00
	s_waitcnt lgkmcnt(6)
	v_mfma_f32_32x32x16_bf16 v[48:63], v[162:165], v[198:201], v[48:63]
	ds_read_b64_tr_b16 v[198:199], v177 offset:0x2400
	ds_read_b64_tr_b16 v[200:201], v177 offset:0x2c00
	s_waitcnt lgkmcnt(6)
	v_mfma_f32_32x32x16_bf16 v[48:63], v[166:169], v[202:205], v[48:63]
	ds_read_b64_tr_b16 v[202:203], v177 offset:0x3400
	ds_read_b64_tr_b16 v[204:205], v177 offset:0x3c00
	s_waitcnt lgkmcnt(6)
	v_mfma_f32_32x32x16_bf16 v[32:47], v[154:157], v[190:193], v[32:47]
	ds_read_b64_tr_b16 v[190:191], v177 offset:0x600
	ds_read_b64_tr_b16 v[192:193], v177 offset:0xe00
	s_waitcnt lgkmcnt(6)
	v_mfma_f32_32x32x16_bf16 v[32:47], v[158:161], v[194:197], v[32:47]
	ds_read_b64_tr_b16 v[194:195], v177 offset:0x1600
	ds_read_b64_tr_b16 v[196:197], v177 offset:0x1e00
	s_waitcnt lgkmcnt(6)
	v_mfma_f32_32x32x16_bf16 v[32:47], v[162:165], v[198:201], v[32:47]
	ds_read_b64_tr_b16 v[198:199], v177 offset:0x2600
	ds_read_b64_tr_b16 v[200:201], v177 offset:0x2e00
	s_waitcnt lgkmcnt(6)
	v_mfma_f32_32x32x16_bf16 v[32:47], v[166:169], v[202:205], v[32:47]
	ds_read_b64_tr_b16 v[202:203], v177 offset:0x3600
	ds_read_b64_tr_b16 v[204:205], v177 offset:0x3e00
	s_waitcnt vmcnt(0)
	s_waitcnt lgkmcnt(0)
	s_barrier
	v_mfma_f32_32x32x16_bf16 v[16:31], v[154:157], v[190:193], v[16:31]
	v_mfma_f32_32x32x16_bf16 v[16:31], v[158:161], v[194:197], v[16:31]
	v_max_f32_e32 v160, v235, v237
	v_sub_f32_e32 v235, v160, v187
	v_mfma_f32_32x32x16_bf16 v[16:31], v[162:165], v[198:201], v[16:31]
	v_mfma_f32_32x32x16_bf16 v[16:31], v[166:169], v[202:205], v[16:31]
	v_cmp_ge_f32_e32 vcc, s65, v235
	s_cmp_eq_u64 vcc, exec
	s_waitcnt vmcnt(0)
	s_cselect_b64 s[38:39], -1, 0
	s_add_i32 s2, s12, -1
	s_cmp_ge_u32 s2, s52
	v_lshl_add_u64 v[158:159], v[150:151], 0, s[82:83]
	v_lshl_add_u64 v[156:157], v[152:153], 0, s[82:83]
	v_lshl_add_u64 v[154:155], v[148:149], 0, s[82:83]

; #define QK_FENCE() __builtin_amdgcn_sched_barrier(0x406)
; DI void partialSM(f32x16& p0, f32x16& p1, float& m_reg, float& mn, float& alpha) {
;     ...
;   const float mnC = -mn * C;
; #pragma unroll
;   for (int r = 0; r < 16; ++r) p0[r] = fmaf(p0[r], C, mnC);
; #pragma unroll
;   for (int r = 0; r < 16; ++r) p1[r] = fmaf(p1[r], C, mnC);
; #pragma unroll
;   for (int r = 0; r < 16; ++r) p0[r] = __builtin_amdgcn_exp2f(p0[r]);
; }
; DI void finishSM(f32x16& p0, f32x16& p1, float alpha, float& l_reg, bf16x8& pa0, bf16x8& pa1, bf16x8& pa2, bf16x8& pa3) {
; #pragma unroll
;   for (int r = 0; r < 16; ++r) p1[r] = __builtin_amdgcn_exp2f(p1[r]);
; DI void qkt12(f32x16& p0, f32x16& p1, const char* Kt, const char* Rt, const int* ko, const int* ro, const bf16x8* qr) {
;   { const f32x16 z = {0.f, 0.f, 0.f, 0.f, 0.f, 0.f, 0.f, 0.f, 0.f, 0.f, 0.f, 0.f, 0.f, 0.f, 0.f, 0.f}; p0 = z; p1 = z; }
;   const char* kp[4] = {Kt + ko[0], Kt + ko[1], Kt + ko[2], Kt + ko[3]};
;   const char* rp[4] = {Rt + ro[0], Rt + ro[1], Rt + ro[2], Rt + ro[3]};
;   bf16x8 ka[2], kb[2];
;   ka[0] = *reinterpret_cast<const bf16x8*>(kp[0]); kb[0] = *reinterpret_cast<const bf16x8*>(kp[0] + 8192);
; #pragma unroll
;   for (int d0 = 0; d0 < 12; ++d0) {
;     if (d0 + 1 < 12) { const int d1 = d0 + 1;
;       if (d1 < 8) { ka[d1 & 1] = *reinterpret_cast<const bf16x8*>(kp[d1 & 3] + (d1 >> 2) * 128); kb[d1 & 1] = *reinterpret_cast<const bf16x8*>(kp[d1 & 3] + (d1 >> 2) * 128 + 8192); }
;       else { ka[d1 & 1] = *reinterpret_cast<const bf16x8*>(rp[d1 - 8]); kb[d1 & 1] = *reinterpret_cast<const bf16x8*>(rp[d1 - 8] + 4096); } }
;     QK_FENCE();
;     p0 = __builtin_amdgcn_mfma_f32_32x32x16_bf16(ka[d0 & 1], qr[d0], p0, 0, 0, 0);
;     p1 = __builtin_amdgcn_mfma_f32_32x32x16_bf16(kb[d0 & 1], qr[d0], p1, 0, 0, 0);
;     QK_FENCE();
;   }
.LBB0_128:
	s_add_i32 s2, s12, -1
	s_cmp_ge_u32 s2, s52
	s_cbranch_scc1 .Lattn_bb2_nodma
	v_cndmask_b32_e64 v160, v160, v187, s[38:39]
	s_add_i32 s2, s42, 0xa000
	s_cmp_lg_u32 s61, 2
	s_cselect_b32 s2, s2, 0
	s_add_i32 s6, s2, 16
	v_add_u32_e32 v213, s6, v176
	ds_read_b128 v[222:225], v213 offset:16384
	v_add_u32_e32 v230, s6, v179
	ds_read_b128 v[226:229], v213 offset:24576
	ds_read_b128 v[214:217], v230 offset:16384
	ds_read_b128 v[218:221], v230 offset:24576
	v_add_u32_e32 v231, s6, v180
	v_add_u32_e32 v234, s6, v181
	v_mul_f32_e32 v197, 0xbdd53b94, v160
	v_fmamk_f32 v161, v94, 0x3dd53b94, v197
	v_fmamk_f32 v194, v80, 0x3dd53b94, v197
	v_fmamk_f32 v196, v81, 0x3dd53b94, v197
	v_fmamk_f32 v192, v82, 0x3dd53b94, v197
	v_fmamk_f32 v195, v83, 0x3dd53b94, v197
	v_fmamk_f32 v187, v84, 0x3dd53b94, v197
	v_fmamk_f32 v193, v85, 0x3dd53b94, v197
	v_fmamk_f32 v169, v86, 0x3dd53b94, v197
	v_fmamk_f32 v190, v87, 0x3dd53b94, v197
	v_fmamk_f32 v166, v88, 0x3dd53b94, v197
	v_fmamk_f32 v168, v89, 0x3dd53b94, v197
	v_fmamk_f32 v164, v90, 0x3dd53b94, v197
	v_fmamk_f32 v167, v91, 0x3dd53b94, v197
	v_fmamk_f32 v162, v92, 0x3dd53b94, v197
	v_fmamk_f32 v165, v93, 0x3dd53b94, v197
	v_fmamk_f32 v163, v95, 0x3dd53b94, v197
	v_fmamk_f32 v208, v74, 0x3dd53b94, v197
	v_fmamk_f32 v209, v75, 0x3dd53b94, v197
	v_fmamk_f32 v198, v64, 0x3dd53b94, v197
	v_fmamk_f32 v199, v65, 0x3dd53b94, v197
	v_fmamk_f32 v200, v66, 0x3dd53b94, v197
	v_fmamk_f32 v201, v67, 0x3dd53b94, v197
	v_fmamk_f32 v202, v68, 0x3dd53b94, v197
	v_fmamk_f32 v203, v69, 0x3dd53b94, v197
	v_fmamk_f32 v204, v70, 0x3dd53b94, v197
	v_fmamk_f32 v205, v71, 0x3dd53b94, v197
	v_fmamk_f32 v206, v72, 0x3dd53b94, v197
	v_fmamk_f32 v207, v73, 0x3dd53b94, v197
	v_fmamk_f32 v210, v76, 0x3dd53b94, v197
	v_fmamk_f32 v211, v77, 0x3dd53b94, v197
	v_fmamk_f32 v212, v78, 0x3dd53b94, v197
	v_fmac_f32_e32 v197, 0x3dd53b94, v79
	v_exp_f32_e32 v161, v161
	s_waitcnt lgkmcnt(3)
	v_mfma_f32_32x32x16_bf16 v[80:95], v[222:225], v[134:137], 0
	v_exp_f32_e32 v194, v194
	v_exp_f32_e32 v196, v196
	v_exp_f32_e32 v192, v192
	s_waitcnt lgkmcnt(2)
	v_mfma_f32_32x32x16_bf16 v[64:79], v[226:229], v[134:137], 0
	ds_read_b128 v[222:225], v231 offset:16384
	ds_read_b128 v[226:229], v231 offset:24576
	v_exp_f32_e32 v195, v195
	v_exp_f32_e32 v187, v187
	v_exp_f32_e32 v193, v193
	s_waitcnt lgkmcnt(3)
	v_mfma_f32_32x32x16_bf16 v[80:95], v[214:217], v[130:133], v[80:95]
	v_add_u32_e32 v240, s44, v178
	v_exp_f32_e32 v169, v169
	v_readfirstlane_b32 s2, v240
	s_mov_b64 s[0:1], 0x1bc00100
	v_lshl_add_u64 v[238:239], v[158:159], 0, s[0:1]
	s_mov_b32 m0, s2
	v_exp_f32_e32 v190, v190
	global_load_lds_dwordx4 v[238:239], off
	s_waitcnt lgkmcnt(2)
	v_mfma_f32_32x32x16_bf16 v[64:79], v[218:221], v[130:133], v[64:79]
	ds_read_b128 v[214:217], v234 offset:16384
	ds_read_b128 v[218:221], v234 offset:24576
	v_exp_f32_e32 v166, v166
	v_exp_f32_e32 v168, v168
	v_exp_f32_e32 v164, v164
	s_waitcnt lgkmcnt(3)
	v_mfma_f32_32x32x16_bf16 v[80:95], v[222:225], v[126:129], v[80:95]
	v_exp_f32_e32 v167, v167
	v_exp_f32_e32 v162, v162
	v_exp_f32_e32 v165, v165
	s_waitcnt lgkmcnt(2)
	v_mfma_f32_32x32x16_bf16 v[64:79], v[226:229], v[126:129], v[64:79]
	ds_read_b128 v[222:225], v213 offset:16512
	ds_read_b128 v[226:229], v213 offset:24704
	v_add_u32_e32 v213, s6, v182
	v_exp_f32_e32 v163, v163
	v_exp_f32_e32 v198, v198
	s_waitcnt lgkmcnt(3)
	v_mfma_f32_32x32x16_bf16 v[80:95], v[214:217], v[114:117], v[80:95]
	v_add_u32_e32 v242, 0x2000, v240
	s_mov_b64 s[0:1], 0x1bc20100
	v_lshl_add_u64 v[238:239], v[158:159], 0, s[0:1]
	v_readfirstlane_b32 s2, v242
	s_mov_b32 m0, s2
	v_exp_f32_e32 v199, v199
	global_load_lds_dwordx4 v[238:239], off
	s_waitcnt lgkmcnt(2)
	v_mfma_f32_32x32x16_bf16 v[64:79], v[218:221], v[114:117], v[64:79]
	ds_read_b128 v[214:217], v230 offset:16512
	ds_read_b128 v[218:221], v230 offset:24704
	v_exp_f32_e32 v200, v200
	v_exp_f32_e32 v201, v201
	v_exp_f32_e32 v202, v202
	s_waitcnt lgkmcnt(3)
	v_mfma_f32_32x32x16_bf16 v[80:95], v[222:225], v[110:113], v[80:95]
	v_exp_f32_e32 v203, v203
	v_exp_f32_e32 v204, v204
	v_exp_f32_e32 v205, v205
	s_waitcnt lgkmcnt(2)
	v_mfma_f32_32x32x16_bf16 v[64:79], v[226:229], v[110:113], v[64:79]
	ds_read_b128 v[222:225], v231 offset:16512
	ds_read_b128 v[226:229], v231 offset:24704
	v_exp_f32_e32 v206, v206
	v_exp_f32_e32 v207, v207
	v_exp_f32_e32 v210, v210
	s_waitcnt lgkmcnt(3)
	v_mfma_f32_32x32x16_bf16 v[80:95], v[214:217], v[106:109], v[80:95]
	v_add_u32_e32 v242, 0x4000, v240
	s_mov_b64 s[0:1], 0x1bc00000
	v_lshl_add_u64 v[238:239], v[156:157], 0, s[0:1]
	v_readfirstlane_b32 s2, v242
	s_mov_b32 m0, s2
	v_exp_f32_e32 v211, v211
	global_load_lds_dwordx4 v[238:239], off
	s_waitcnt lgkmcnt(2)
	v_mfma_f32_32x32x16_bf16 v[64:79], v[218:221], v[106:109], v[64:79]
	ds_read_b128 v[214:217], v234 offset:16512
	ds_read_b128 v[218:221], v234 offset:24704
	v_exp_f32_e32 v212, v212
	v_exp_f32_e32 v235, v208
	v_exp_f32_e32 v237, v197
	s_waitcnt lgkmcnt(3)
	v_mfma_f32_32x32x16_bf16 v[80:95], v[222:225], v[102:105], v[80:95]
	v_add_f32_e32 v197, 0, v194
	v_add_f32_e32 v197, v196, v197
	v_add_f32_e32 v197, v192, v197
	v_add_f32_e32 v197, v195, v197
	v_add_f32_e32 v197, v187, v197
	v_add_f32_e32 v197, v193, v197
	s_waitcnt lgkmcnt(2)
	v_mfma_f32_32x32x16_bf16 v[64:79], v[226:229], v[102:105], v[64:79]
	ds_read_b128 v[222:225], v213 offset:32768
	ds_read_b128 v[226:229], v213 offset:36864
	v_add_u32_e32 v213, s6, v183
	v_add_f32_e32 v197, v169, v197
	v_add_f32_e32 v197, v190, v197
	v_add_f32_e32 v197, v166, v197
	v_add_f32_e32 v197, v168, v197
	v_add_f32_e32 v197, v164, v197
	s_waitcnt lgkmcnt(3)
; DI void finishSM(f32x16& p0, f32x16& p1, float alpha, float& l_reg, bf16x8& pa0, bf16x8& pa1, bf16x8& pa2, bf16x8& pa3) {
; #pragma unroll
;   for (int r = 0; r < 16; ++r) p1[r] = __builtin_amdgcn_exp2f(p1[r]);
;   float ps = 0;
; #pragma unroll
;   for (int r = 0; r < 16; ++r) ps += p0[r];
; #pragma unroll
;   for (int r = 0; r < 16; ++r) ps += p1[r];
;   { auto rr = __builtin_amdgcn_permlane32_swap(__float_as_uint(ps), __float_as_uint(ps), false, false);
;     ps = __uint_as_float(rr[0]) + __uint_as_float(rr[1]); }
;   l_reg = l_reg * alpha + ps;
;     ...
;   PK4(p0, 0, pa0); PK4(p0, 8, pa1); PK4(p1, 0, pa2); PK4(p1, 8, pa3);
;     ...
; }
; DI void qkt(f32x16& p0, f32x16& p1, const char* Ks, const char* Rs, const bf16x8* qr, const char* qrl, int r32, int hi) {
;   { const f32x16 z = {0.f, 0.f, 0.f, 0.f, 0.f, 0.f, 0.f, 0.f, 0.f, 0.f, 0.f, 0.f, 0.f, 0.f, 0.f, 0.f}; p0 = z; p1 = z; }
; #pragma unroll
;   for (int d0 = 0; d0 < 8; ++d0) { const int cb = (d0 * 16 + hi * 8) * 2;
;     bf16x8 b0 = *reinterpret_cast<const bf16x8*>(Ks + KSWZ(r32, cb));
;     bf16x8 b1 = *reinterpret_cast<const bf16x8*>(Ks + KSWZ(32 + r32, cb));
;     p0 = __builtin_amdgcn_mfma_f32_32x32x16_bf16(b0, qr[d0], p0, 0, 0, 0);
;     p1 = __builtin_amdgcn_mfma_f32_32x32x16_bf16(b1, qr[d0], p1, 0, 0, 0); }
; #pragma unroll
;   for (int d0 = 0; d0 < 4; ++d0) { const int cb = (d0 * 16 + hi * 8) * 2;
;     bf16x8 b0 = *reinterpret_cast<const bf16x8*>(Rs + RSWZ(r32, cb));
;     bf16x8 b1 = *reinterpret_cast<const bf16x8*>(Rs + RSWZ(32 + r32, cb));
;     const bf16x8 qv = *reinterpret_cast<const bf16x8*>(qrl + d0 * 1024);
;     p0 = __builtin_amdgcn_mfma_f32_32x32x16_bf16(b0, qv, p0, 0, 0, 0);
;     p1 = __builtin_amdgcn_mfma_f32_32x32x16_bf16(b1, qv, p1, 0, 0, 0); }
; }
; DI int v_st(int k, int c) { const int kk = (k & ~0xC) | ((k & 4) << 1) | ((k & 8) >> 1); return ((kk >> 3) * 4 + (c >> 5)) * 512 + ((kk & 7) * 32 + (c & 31)) * 2; }
; DI int v_rd_base(int lane) { return ((lane & 3) << 3) | (((lane >> 2) & 3) << 6) | (((lane >> 4) & 1) << 5) | (((lane >> 5) & 1) << 8); }
; template <int OFF> DI s16x4 tr_read(int vb) { s16x4 r; asm volatile("ds_read_b64_tr_b16 %0, %1 offset:%2" : "=&v"(r) : "v"(vb), "i"(OFF) : "memory"); return r; }
; template <int D0> DI void pv_one(f32x16& od, int vb, bf16x8 pa0, bf16x8 pa1, bf16x8 pa2, bf16x8 pa3) {
	v_mfma_f32_32x32x16_bf16 v[80:95], v[214:217], v[98:101], v[80:95]
	v_add_u32_e32 v242, 0x6000, v240
	s_mov_b64 s[0:1], 0x1bc20000
	v_lshl_add_u64 v[238:239], v[156:157], 0, s[0:1]
	v_readfirstlane_b32 s2, v242
	s_mov_b32 m0, s2
	v_add_f32_e32 v197, v167, v197
	global_load_lds_dwordx4 v[238:239], off
	v_add_f32_e32 v197, v162, v197
	v_add_f32_e32 v197, v165, v197
	s_waitcnt lgkmcnt(2)
	v_mfma_f32_32x32x16_bf16 v[64:79], v[218:221], v[98:101], v[64:79]
	ds_read_b128 v[214:217], v213 offset:32768
	ds_read_b128 v[218:221], v213 offset:36864
	v_add_u32_e32 v213, s6, v184
	v_add_f32_e32 v197, v161, v197
	v_add_f32_e32 v197, v163, v197
	v_add_f32_e32 v197, v198, v197
	v_add_f32_e32 v197, v199, v197
	v_add_f32_e32 v197, v200, v197
	s_waitcnt lgkmcnt(3)
	v_mfma_f32_32x32x16_bf16 v[80:95], v[222:225], v[122:125], v[80:95]
	v_add_f32_e32 v197, v201, v197
	v_add_f32_e32 v197, v202, v197
	v_add_f32_e32 v197, v203, v197
	v_add_f32_e32 v197, v204, v197
	v_exp_f32_e32 v241, v209
	s_waitcnt lgkmcnt(2)
	v_mfma_f32_32x32x16_bf16 v[64:79], v[226:229], v[122:125], v[64:79]
	ds_read_b128 v[222:225], v213 offset:32768
	ds_read_b128 v[226:229], v213 offset:36864
	v_add_u32_e32 v213, s6, v185
	v_add_f32_e32 v197, v205, v197
	v_add_f32_e32 v197, v206, v197
	v_add_f32_e32 v197, v207, v197
	v_add_f32_e32 v197, v235, v197
	v_add_f32_e32 v197, v241, v197
	s_waitcnt lgkmcnt(3)
	v_mfma_f32_32x32x16_bf16 v[80:95], v[214:217], v[142:145], v[80:95]
	v_add_u32_e32 v242, 0x8000, v240
	s_mov_b64 s[0:1], 0x1fb46000
	v_lshl_add_u64 v[238:239], v[154:155], 0, s[0:1]
	v_readfirstlane_b32 s2, v242
	s_mov_b32 m0, s2
	v_add_f32_e32 v197, v210, v197
	global_load_lds_dwordx4 v[238:239], off
	s_movk_i32 s0, 0x410
	s_movk_i32 s1, 0x1800
	v_add_f32_e32 v197, v211, v197
	v_add_f32_e32 v197, v212, v197
	s_waitcnt lgkmcnt(2)
	v_mfma_f32_32x32x16_bf16 v[64:79], v[218:221], v[142:145], v[64:79]
	ds_read_b128 v[214:217], v213 offset:32768
	ds_read_b128 v[218:221], v213 offset:36864
	v_add_f32_e32 v208, v237, v197
	v_mov_b32_e32 v209, v208
	v_cvt_pk_bf16_f32 v194, v194, v196
	v_cvt_pk_bf16_f32 v195, v192, v195
	v_permlane32_swap_b32_e32 v208, v209
	v_cvt_pk_bf16_f32 v196, v187, v193
	s_waitcnt lgkmcnt(3)
	v_mfma_f32_32x32x16_bf16 v[80:95], v[222:225], v[118:121], v[80:95]
	v_cvt_pk_bf16_f32 v197, v169, v190
	v_cvt_pk_bf16_f32 v166, v166, v168
	v_cvt_pk_bf16_f32 v167, v164, v167
	v_cvt_pk_bf16_f32 v168, v162, v165
	v_cvt_pk_bf16_f32 v169, v161, v163
	v_cvt_pk_bf16_f32 v162, v198, v199
	s_waitcnt lgkmcnt(2)
	v_mfma_f32_32x32x16_bf16 v[64:79], v[226:229], v[118:121], v[64:79]
	v_cvt_pk_bf16_f32 v163, v200, v201
	v_cvt_pk_bf16_f32 v164, v202, v203
	v_cvt_pk_bf16_f32 v165, v204, v205
	v_cvt_pk_bf16_f32 v198, v206, v207
	v_cvt_pk_bf16_f32 v199, v235, v241
	v_cvt_pk_bf16_f32 v200, v210, v211
	s_waitcnt lgkmcnt(1)
	v_mfma_f32_32x32x16_bf16 v[80:95], v[214:217], v[138:141], v[80:95]
	v_cvt_pk_bf16_f32 v201, v212, v237
	v_permlane32_swap_b32_e32 v194, v196
	v_permlane32_swap_b32_e32 v195, v197
	v_permlane32_swap_b32_e32 v166, v168
	v_permlane32_swap_b32_e32 v167, v169
	v_permlane32_swap_b32_e32 v162, v164
	s_waitcnt lgkmcnt(0)
	v_mfma_f32_32x32x16_bf16 v[64:79], v[218:221], v[138:141], v[64:79]
	v_add_u32_e32 v161, s42, v174
	ds_read_b64_tr_b16 v[202:203], v161 offset:0
	ds_read_b64_tr_b16 v[204:205], v161 offset:0x800
	ds_read_b64_tr_b16 v[210:211], v161 offset:0x1000
	ds_read_b64_tr_b16 v[212:213], v161 offset:0x1800
	ds_read_b64_tr_b16 v[214:215], v161 offset:0x2000
	ds_read_b64_tr_b16 v[216:217], v161 offset:0x2800
	ds_read_b64_tr_b16 v[218:219], v161 offset:0x3000
	ds_read_b64_tr_b16 v[220:221], v161 offset:0x3800
	v_permlane32_swap_b32_e32 v163, v165
	v_permlane32_swap_b32_e32 v198, v200
	v_permlane32_swap_b32_e32 v199, v201
	v_max_f32_e32 v235, v81, v81
	v_max_f32_e32 v237, v80, v80
	s_waitcnt lgkmcnt(6)
	v_mfma_f32_32x32x16_bf16 v[0:15], v[194:197], v[202:205], v[0:15]
	ds_read_b64_tr_b16 v[202:203], v161 offset:0x200
	ds_read_b64_tr_b16 v[204:205], v161 offset:0xa00
	v_max_f32_e32 v235, v237, v235
	v_max3_f32 v235, v235, v82, v83
	v_max3_f32 v235, v235, v84, v85
	v_max3_f32 v235, v235, v86, v87
	v_max3_f32 v235, v235, v88, v89
	v_max3_f32 v235, v235, v90, v91
	s_waitcnt lgkmcnt(6)
	v_mfma_f32_32x32x16_bf16 v[0:15], v[166:169], v[210:213], v[0:15]
	ds_read_b64_tr_b16 v[210:211], v161 offset:0x1200
	ds_read_b64_tr_b16 v[212:213], v161 offset:0x1a00
	v_max3_f32 v235, v235, v92, v93
	v_max3_f32 v235, v235, v94, v95
	v_max3_f32 v235, v235, v64, v65
	v_max3_f32 v235, v235, v66, v67
	v_max3_f32 v235, v235, v68, v69
	v_max3_f32 v235, v235, v70, v71
	s_waitcnt lgkmcnt(6)
	v_mfma_f32_32x32x16_bf16 v[0:15], v[162:165], v[214:217], v[0:15]
	ds_read_b64_tr_b16 v[214:215], v161 offset:0x2200
	ds_read_b64_tr_b16 v[216:217], v161 offset:0x2a00
	v_max3_f32 v235, v235, v72, v73
	v_max3_f32 v235, v235, v74, v75
	v_max3_f32 v235, v235, v76, v77
	v_max3_f32 v235, v235, v78, v79
	v_mov_b32_e32 v237, v235
	s_waitcnt lgkmcnt(6)
	v_mfma_f32_32x32x16_bf16 v[0:15], v[198:201], v[218:221], v[0:15]
	ds_read_b64_tr_b16 v[218:219], v161 offset:0x3200
	ds_read_b64_tr_b16 v[220:221], v161 offset:0x3a00
	v_permlane32_swap_b32_e32 v235, v237
	v_max_f32_e32 v237, v237, v237
	v_max_f32_e32 v235, v235, v235
	s_waitcnt lgkmcnt(6)
	v_mfma_f32_32x32x16_bf16 v[48:63], v[194:197], v[202:205], v[48:63]
	ds_read_b64_tr_b16 v[202:203], v161 offset:0x400
	ds_read_b64_tr_b16 v[204:205], v161 offset:0xc00
	s_waitcnt lgkmcnt(6)
	v_mfma_f32_32x32x16_bf16 v[48:63], v[166:169], v[210:213], v[48:63]
	ds_read_b64_tr_b16 v[210:211], v161 offset:0x1400
	ds_read_b64_tr_b16 v[212:213], v161 offset:0x1c00
	s_waitcnt lgkmcnt(6)
	v_mfma_f32_32x32x16_bf16 v[48:63], v[162:165], v[214:217], v[48:63]
	ds_read_b64_tr_b16 v[214:215], v161 offset:0x2400
	ds_read_b64_tr_b16 v[216:217], v161 offset:0x2c00
	s_waitcnt lgkmcnt(6)
	v_mfma_f32_32x32x16_bf16 v[48:63], v[198:201], v[218:221], v[48:63]
	ds_read_b64_tr_b16 v[218:219], v161 offset:0x3400
	ds_read_b64_tr_b16 v[220:221], v161 offset:0x3c00
	s_waitcnt lgkmcnt(6)
	v_mfma_f32_32x32x16_bf16 v[32:47], v[194:197], v[202:205], v[32:47]
	ds_read_b64_tr_b16 v[202:203], v161 offset:0x600
	ds_read_b64_tr_b16 v[204:205], v161 offset:0xe00
	s_waitcnt lgkmcnt(6)
	v_mfma_f32_32x32x16_bf16 v[32:47], v[166:169], v[210:213], v[32:47]
	ds_read_b64_tr_b16 v[210:211], v161 offset:0x1600
	ds_read_b64_tr_b16 v[212:213], v161 offset:0x1e00
	s_waitcnt lgkmcnt(6)
	v_mfma_f32_32x32x16_bf16 v[32:47], v[162:165], v[214:217], v[32:47]
	ds_read_b64_tr_b16 v[214:215], v161 offset:0x2600
	ds_read_b64_tr_b16 v[216:217], v161 offset:0x2e00
	s_waitcnt lgkmcnt(6)
	v_mfma_f32_32x32x16_bf16 v[32:47], v[198:201], v[218:221], v[32:47]
	ds_read_b64_tr_b16 v[218:219], v161 offset:0x3600
	ds_read_b64_tr_b16 v[220:221], v161 offset:0x3e00
	v_max_f32_e32 v161, v235, v237
	v_sub_f32_e32 v237, v161, v160
	s_waitcnt vmcnt(0)
	s_waitcnt vmcnt(0)
	s_waitcnt lgkmcnt(0)
	s_barrier
; #define SBAR() __builtin_amdgcn_sched_barrier(0)
; template <int OFF> DI s16x4 tr_read(int vb) { s16x4 r; asm volatile("ds_read_b64_tr_b16 %0, %1 offset:%2" : "=&v"(r) : "v"(vb), "i"(OFF) : "memory"); return r; }
; #define VWAIT() asm volatile("s_waitcnt vmcnt(0)" ::: "memory")
; template <int D0> DI void pv_one(f32x16& od, int vb, bf16x8 pa0, bf16x8 pa1, bf16x8 pa2, bf16x8 pa3) {
;   const s16x4 l0 = tr_read<v_rd_off(D0, 0, 0)>(vb), h0 = tr_read<v_rd_off(D0, 0, 1)>(vb), l1 = tr_read<v_rd_off(D0, 1, 0)>(vb), h1 = tr_read<v_rd_off(D0, 1, 1)>(vb);
;   const s16x4 l2 = tr_read<v_rd_off(D0, 2, 0)>(vb), h2 = tr_read<v_rd_off(D0, 2, 1)>(vb), l3 = tr_read<v_rd_off(D0, 3, 0)>(vb), h3 = tr_read<v_rd_off(D0, 3, 1)>(vb);
;   asm volatile("s_waitcnt lgkmcnt(0)" ::: "memory"); SBAR();
;     ...
;   od = __builtin_amdgcn_mfma_f32_32x32x16_bf16(pa0, PK(l0, h0), od, 0, 0, 0);
;   od = __builtin_amdgcn_mfma_f32_32x32x16_bf16(pa1, PK(l1, h1), od, 0, 0, 0);
;   od = __builtin_amdgcn_mfma_f32_32x32x16_bf16(pa2, PK(l2, h2), od, 0, 0, 0);
;   od = __builtin_amdgcn_mfma_f32_32x32x16_bf16(pa3, PK(l3, h3), od, 0, 0, 0);
;     ...
; }
; DI void pv_d0(f32x16* o, int vb, bf16x8 pa0, bf16x8 pa1, bf16x8 pa2, bf16x8 pa3) {
;   pv_one<0>(o[0], vb, pa0, pa1, pa2, pa3); pv_one<1>(o[1], vb, pa0, pa1, pa2, pa3); pv_one<2>(o[2], vb, pa0, pa1, pa2, pa3); pv_one<3>(o[3], vb, pa0, pa1, pa2, pa3);
; DI void attn_item_dma(const u16* Qb, const u16* Kh, const u16* Vh, const u16* Rh, u16* Ob, int seq, const float* rope, int pos0, char* lds) {
;     ...
;   for (int j = 1; j + 1 < NT; j += 2) {
;     const int sp = PRV(sj), sn = NXT(sj);
;     SBAR(); qkt12(pB0, pB1, lds + sj * STG + 16384, lds + sj * STG + 32768, ko, ro, qr);
;     finishSM(pA0, pA1, alA, l_reg, pa0, pa1, pa2, pa3); SBAR();
;     pv_d0(o, vb0 + sp * STG, pa0, pa1, pa2, pa3); partialSM(pB0, pB1, m_reg, mnB, alB);
;     VWAIT(); __syncthreads();
;     if (j + 2 < NT) DMA(j + 2, sp);
;     RESC(alB);
;     SBAR(); qkt12(pA0, pA1, lds + sn * STG + 16384, lds + sn * STG + 32768, ko, ro, qr);
;     finishSM(pB0, pB1, alB, l_reg, pa0, pa1, pa2, pa3); SBAR();
;     pv_d0(o, vb0 + sj * STG, pa0, pa1, pa2, pa3); partialSM(pA0, pA1, m_reg, mnA, alA);
;     VWAIT(); __syncthreads();
;     if (j + 3 < NT) DMA(j + 3, sj);
;     RESC(alA);
	v_mfma_f32_32x32x16_bf16 v[16:31], v[194:197], v[202:205], v[16:31]
	v_mfma_f32_32x32x16_bf16 v[16:31], v[166:169], v[210:213], v[16:31]
	v_mfma_f32_32x32x16_bf16 v[16:31], v[162:165], v[214:217], v[16:31]
	v_mfma_f32_32x32x16_bf16 v[16:31], v[198:201], v[218:221], v[16:31]
	v_cmp_ge_f32_e32 vcc, s65, v237
	s_cmp_eq_u64 vcc, exec
	s_cselect_b64 s[38:39], -1, 0
	s_cmp_ge_u32 s12, s52
	s_cselect_b64 s[42:43], -1, 0
	s_and_b64 vcc, exec, s[42:43]
	s_branch .Lattn_bb2_join
.Lattn_bb2_nodma:
	v_cndmask_b32_e64 v160, v160, v187, s[38:39]
	s_add_i32 s2, s42, 0xa000
	s_cmp_lg_u32 s61, 2
	s_cselect_b32 s2, s2, 0
	s_add_i32 s6, s2, 16
	v_add_u32_e32 v213, s6, v176
	ds_read_b128 v[222:225], v213 offset:16384
	v_add_u32_e32 v230, s6, v179
	ds_read_b128 v[226:229], v213 offset:24576
	ds_read_b128 v[214:217], v230 offset:16384
	ds_read_b128 v[218:221], v230 offset:24576
	v_add_u32_e32 v231, s6, v180
	v_add_u32_e32 v234, s6, v181
	v_mul_f32_e32 v197, 0xbdd53b94, v160
	v_fmamk_f32 v161, v94, 0x3dd53b94, v197
	v_fmamk_f32 v194, v80, 0x3dd53b94, v197
	v_fmamk_f32 v196, v81, 0x3dd53b94, v197
	v_fmamk_f32 v192, v82, 0x3dd53b94, v197
	v_fmamk_f32 v195, v83, 0x3dd53b94, v197
	v_fmamk_f32 v187, v84, 0x3dd53b94, v197
	v_fmamk_f32 v193, v85, 0x3dd53b94, v197
	v_fmamk_f32 v169, v86, 0x3dd53b94, v197
	v_fmamk_f32 v190, v87, 0x3dd53b94, v197
	v_fmamk_f32 v166, v88, 0x3dd53b94, v197
	v_fmamk_f32 v168, v89, 0x3dd53b94, v197
	v_fmamk_f32 v164, v90, 0x3dd53b94, v197
	v_fmamk_f32 v167, v91, 0x3dd53b94, v197
	v_fmamk_f32 v162, v92, 0x3dd53b94, v197
	v_fmamk_f32 v165, v93, 0x3dd53b94, v197
	v_fmamk_f32 v163, v95, 0x3dd53b94, v197
	v_fmamk_f32 v208, v74, 0x3dd53b94, v197
	v_fmamk_f32 v209, v75, 0x3dd53b94, v197
	v_fmamk_f32 v198, v64, 0x3dd53b94, v197
	v_fmamk_f32 v199, v65, 0x3dd53b94, v197
	v_fmamk_f32 v200, v66, 0x3dd53b94, v197
	v_fmamk_f32 v201, v67, 0x3dd53b94, v197
	v_fmamk_f32 v202, v68, 0x3dd53b94, v197
	v_fmamk_f32 v203, v69, 0x3dd53b94, v197
	v_fmamk_f32 v204, v70, 0x3dd53b94, v197
	v_fmamk_f32 v205, v71, 0x3dd53b94, v197
	v_fmamk_f32 v206, v72, 0x3dd53b94, v197
	v_fmamk_f32 v207, v73, 0x3dd53b94, v197
	v_fmamk_f32 v210, v76, 0x3dd53b94, v197
	v_fmamk_f32 v211, v77, 0x3dd53b94, v197
	v_fmamk_f32 v212, v78, 0x3dd53b94, v197
	v_fmac_f32_e32 v197, 0x3dd53b94, v79
	v_exp_f32_e32 v161, v161
	s_waitcnt lgkmcnt(3)
	v_mfma_f32_32x32x16_bf16 v[80:95], v[222:225], v[134:137], 0
	v_exp_f32_e32 v194, v194
	v_exp_f32_e32 v196, v196
	v_exp_f32_e32 v192, v192
	s_waitcnt lgkmcnt(2)
	v_mfma_f32_32x32x16_bf16 v[64:79], v[226:229], v[134:137], 0
	ds_read_b128 v[222:225], v231 offset:16384
	ds_read_b128 v[226:229], v231 offset:24576
	v_exp_f32_e32 v195, v195
	v_exp_f32_e32 v187, v187
	v_exp_f32_e32 v193, v193
	s_waitcnt lgkmcnt(3)
	v_mfma_f32_32x32x16_bf16 v[80:95], v[214:217], v[130:133], v[80:95]
	v_exp_f32_e32 v169, v169
	v_exp_f32_e32 v190, v190
	v_exp_f32_e32 v166, v166
	s_waitcnt lgkmcnt(2)
	v_mfma_f32_32x32x16_bf16 v[64:79], v[218:221], v[130:133], v[64:79]
	ds_read_b128 v[214:217], v234 offset:16384
	ds_read_b128 v[218:221], v234 offset:24576
	v_exp_f32_e32 v168, v168
	v_exp_f32_e32 v164, v164
	v_exp_f32_e32 v167, v167
	s_waitcnt lgkmcnt(3)
	v_mfma_f32_32x32x16_bf16 v[80:95], v[222:225], v[126:129], v[80:95]
	v_exp_f32_e32 v162, v162
	v_exp_f32_e32 v165, v165
	v_exp_f32_e32 v163, v163
	s_waitcnt lgkmcnt(2)
	v_mfma_f32_32x32x16_bf16 v[64:79], v[226:229], v[126:129], v[64:79]
	ds_read_b128 v[222:225], v213 offset:16512
	ds_read_b128 v[226:229], v213 offset:24704
	v_add_u32_e32 v213, s6, v182
	v_exp_f32_e32 v198, v198
	v_exp_f32_e32 v199, v199
	s_waitcnt lgkmcnt(3)
	v_mfma_f32_32x32x16_bf16 v[80:95], v[214:217], v[114:117], v[80:95]
	v_exp_f32_e32 v200, v200
	v_exp_f32_e32 v201, v201
	v_exp_f32_e32 v202, v202
	s_waitcnt lgkmcnt(2)
	v_mfma_f32_32x32x16_bf16 v[64:79], v[218:221], v[114:117], v[64:79]
	ds_read_b128 v[214:217], v230 offset:16512
	ds_read_b128 v[218:221], v230 offset:24704
	v_exp_f32_e32 v203, v203
	v_exp_f32_e32 v204, v204
	v_exp_f32_e32 v205, v205
	s_waitcnt lgkmcnt(3)
	v_mfma_f32_32x32x16_bf16 v[80:95], v[222:225], v[110:113], v[80:95]
	v_exp_f32_e32 v206, v206
	v_exp_f32_e32 v207, v207
	v_exp_f32_e32 v210, v210
	s_waitcnt lgkmcnt(2)
	v_mfma_f32_32x32x16_bf16 v[64:79], v[226:229], v[110:113], v[64:79]
	ds_read_b128 v[222:225], v231 offset:16512
	ds_read_b128 v[226:229], v231 offset:24704
	v_exp_f32_e32 v211, v211
	v_exp_f32_e32 v212, v212
	v_exp_f32_e32 v235, v208
	s_waitcnt lgkmcnt(3)
	v_mfma_f32_32x32x16_bf16 v[80:95], v[214:217], v[106:109], v[80:95]
	v_exp_f32_e32 v237, v197
	v_add_f32_e32 v197, 0, v194
	v_add_f32_e32 v197, v196, v197
	v_add_f32_e32 v197, v192, v197
	v_add_f32_e32 v197, v195, v197
	s_waitcnt lgkmcnt(2)
	v_mfma_f32_32x32x16_bf16 v[64:79], v[218:221], v[106:109], v[64:79]
	ds_read_b128 v[214:217], v234 offset:16512
	ds_read_b128 v[218:221], v234 offset:24704
	v_add_f32_e32 v197, v187, v197
	v_add_f32_e32 v197, v193, v197
	v_add_f32_e32 v197, v169, v197
	v_add_f32_e32 v197, v190, v197
	v_add_f32_e32 v197, v166, v197
	v_add_f32_e32 v197, v168, v197
	s_waitcnt lgkmcnt(3)
	v_mfma_f32_32x32x16_bf16 v[80:95], v[222:225], v[102:105], v[80:95]
	v_add_f32_e32 v197, v164, v197
	v_add_f32_e32 v197, v167, v197
	v_add_f32_e32 v197, v162, v197
	v_add_f32_e32 v197, v165, v197
	v_add_f32_e32 v197, v161, v197
	v_add_f32_e32 v197, v163, v197
	s_waitcnt lgkmcnt(2)
	v_mfma_f32_32x32x16_bf16 v[64:79], v[226:229], v[102:105], v[64:79]
	ds_read_b128 v[222:225], v213 offset:32768
	ds_read_b128 v[226:229], v213 offset:36864
	v_add_u32_e32 v213, s6, v183
	v_add_f32_e32 v197, v198, v197
	v_add_f32_e32 v197, v199, v197
	v_add_f32_e32 v197, v200, v197
	v_add_f32_e32 v197, v201, v197
	v_add_f32_e32 v197, v202, v197
	s_waitcnt lgkmcnt(3)
; DI void finishSM(f32x16& p0, f32x16& p1, float alpha, float& l_reg, bf16x8& pa0, bf16x8& pa1, bf16x8& pa2, bf16x8& pa3) {
; #pragma unroll
;   for (int r = 0; r < 16; ++r) p1[r] = __builtin_amdgcn_exp2f(p1[r]);
;   float ps = 0;
; #pragma unroll
;   for (int r = 0; r < 16; ++r) ps += p0[r];
; #pragma unroll
;   for (int r = 0; r < 16; ++r) ps += p1[r];
;   { auto rr = __builtin_amdgcn_permlane32_swap(__float_as_uint(ps), __float_as_uint(ps), false, false);
;     ps = __uint_as_float(rr[0]) + __uint_as_float(rr[1]); }
;   l_reg = l_reg * alpha + ps;
;     ...
;   PK4(p0, 0, pa0); PK4(p0, 8, pa1); PK4(p1, 0, pa2); PK4(p1, 8, pa3);
;     ...
; }
; DI void qkt(f32x16& p0, f32x16& p1, const char* Ks, const char* Rs, const bf16x8* qr, const char* qrl, int r32, int hi) {
;   { const f32x16 z = {0.f, 0.f, 0.f, 0.f, 0.f, 0.f, 0.f, 0.f, 0.f, 0.f, 0.f, 0.f, 0.f, 0.f, 0.f, 0.f}; p0 = z; p1 = z; }
; #pragma unroll
;   for (int d0 = 0; d0 < 8; ++d0) { const int cb = (d0 * 16 + hi * 8) * 2;
;     bf16x8 b0 = *reinterpret_cast<const bf16x8*>(Ks + KSWZ(r32, cb));
;     bf16x8 b1 = *reinterpret_cast<const bf16x8*>(Ks + KSWZ(32 + r32, cb));
;     p0 = __builtin_amdgcn_mfma_f32_32x32x16_bf16(b0, qr[d0], p0, 0, 0, 0);
;     p1 = __builtin_amdgcn_mfma_f32_32x32x16_bf16(b1, qr[d0], p1, 0, 0, 0); }
; #pragma unroll
;   for (int d0 = 0; d0 < 4; ++d0) { const int cb = (d0 * 16 + hi * 8) * 2;
;     bf16x8 b0 = *reinterpret_cast<const bf16x8*>(Rs + RSWZ(r32, cb));
;     bf16x8 b1 = *reinterpret_cast<const bf16x8*>(Rs + RSWZ(32 + r32, cb));
;     const bf16x8 qv = *reinterpret_cast<const bf16x8*>(qrl + d0 * 1024);
;     p0 = __builtin_amdgcn_mfma_f32_32x32x16_bf16(b0, qv, p0, 0, 0, 0);
;     p1 = __builtin_amdgcn_mfma_f32_32x32x16_bf16(b1, qv, p1, 0, 0, 0); }
; }
; DI int v_st(int k, int c) { const int kk = (k & ~0xC) | ((k & 4) << 1) | ((k & 8) >> 1); return ((kk >> 3) * 4 + (c >> 5)) * 512 + ((kk & 7) * 32 + (c & 31)) * 2; }
; DI int v_rd_base(int lane) { return ((lane & 3) << 3) | (((lane >> 2) & 3) << 6) | (((lane >> 4) & 1) << 5) | (((lane >> 5) & 1) << 8); }
; template <int OFF> DI s16x4 tr_read(int vb) { s16x4 r; asm volatile("ds_read_b64_tr_b16 %0, %1 offset:%2" : "=&v"(r) : "v"(vb), "i"(OFF) : "memory"); return r; }
; template <int D0> DI void pv_one(f32x16& od, int vb, bf16x8 pa0, bf16x8 pa1, bf16x8 pa2, bf16x8 pa3) {
	v_mfma_f32_32x32x16_bf16 v[80:95], v[214:217], v[98:101], v[80:95]
	v_add_f32_e32 v197, v203, v197
	v_add_f32_e32 v197, v204, v197
	v_exp_f32_e32 v241, v209
	v_add_f32_e32 v197, v205, v197
	v_add_f32_e32 v197, v206, v197
	s_waitcnt lgkmcnt(2)
	v_mfma_f32_32x32x16_bf16 v[64:79], v[218:221], v[98:101], v[64:79]
	ds_read_b128 v[214:217], v213 offset:32768
	ds_read_b128 v[218:221], v213 offset:36864
	v_add_u32_e32 v213, s6, v184
	v_add_f32_e32 v197, v207, v197
	v_add_f32_e32 v197, v235, v197
	v_add_f32_e32 v197, v241, v197
	v_add_f32_e32 v197, v210, v197
	v_add_f32_e32 v197, v211, v197
	s_waitcnt lgkmcnt(3)
	v_mfma_f32_32x32x16_bf16 v[80:95], v[222:225], v[122:125], v[80:95]
	v_add_f32_e32 v197, v212, v197
	v_add_f32_e32 v208, v237, v197
	v_mov_b32_e32 v209, v208
	v_cvt_pk_bf16_f32 v194, v194, v196
	v_cvt_pk_bf16_f32 v195, v192, v195
	v_permlane32_swap_b32_e32 v208, v209
	s_waitcnt lgkmcnt(2)
	v_mfma_f32_32x32x16_bf16 v[64:79], v[226:229], v[122:125], v[64:79]
	ds_read_b128 v[222:225], v213 offset:32768
	ds_read_b128 v[226:229], v213 offset:36864
	v_add_u32_e32 v213, s6, v185
	v_cvt_pk_bf16_f32 v196, v187, v193
	v_cvt_pk_bf16_f32 v197, v169, v190
	v_cvt_pk_bf16_f32 v166, v166, v168
	v_cvt_pk_bf16_f32 v167, v164, v167
	v_cvt_pk_bf16_f32 v168, v162, v165
	s_waitcnt lgkmcnt(3)
	v_mfma_f32_32x32x16_bf16 v[80:95], v[214:217], v[142:145], v[80:95]
	v_cvt_pk_bf16_f32 v169, v161, v163
	v_cvt_pk_bf16_f32 v162, v198, v199
	v_cvt_pk_bf16_f32 v163, v200, v201
	v_cvt_pk_bf16_f32 v164, v202, v203
	v_cvt_pk_bf16_f32 v165, v204, v205
	v_cvt_pk_bf16_f32 v198, v206, v207
	s_waitcnt lgkmcnt(2)
	v_mfma_f32_32x32x16_bf16 v[64:79], v[218:221], v[142:145], v[64:79]
	ds_read_b128 v[214:217], v213 offset:32768
	ds_read_b128 v[218:221], v213 offset:36864
	v_cvt_pk_bf16_f32 v199, v235, v241
	v_cvt_pk_bf16_f32 v200, v210, v211
	v_cvt_pk_bf16_f32 v201, v212, v237
	v_permlane32_swap_b32_e32 v194, v196
	v_permlane32_swap_b32_e32 v195, v197
	v_permlane32_swap_b32_e32 v166, v168
	s_waitcnt lgkmcnt(3)
	v_mfma_f32_32x32x16_bf16 v[80:95], v[222:225], v[118:121], v[80:95]
	v_permlane32_swap_b32_e32 v167, v169
	v_permlane32_swap_b32_e32 v162, v164
	v_permlane32_swap_b32_e32 v163, v165
	v_permlane32_swap_b32_e32 v198, v200
	v_permlane32_swap_b32_e32 v199, v201
	s_waitcnt lgkmcnt(2)
	v_mfma_f32_32x32x16_bf16 v[64:79], v[226:229], v[118:121], v[64:79]
	s_waitcnt lgkmcnt(1)
	v_mfma_f32_32x32x16_bf16 v[80:95], v[214:217], v[138:141], v[80:95]
	s_waitcnt lgkmcnt(0)
	v_mfma_f32_32x32x16_bf16 v[64:79], v[218:221], v[138:141], v[64:79]
	v_add_u32_e32 v161, s42, v174
	ds_read_b64_tr_b16 v[202:203], v161 offset:0
	ds_read_b64_tr_b16 v[204:205], v161 offset:0x800
	ds_read_b64_tr_b16 v[210:211], v161 offset:0x1000
	ds_read_b64_tr_b16 v[212:213], v161 offset:0x1800
	ds_read_b64_tr_b16 v[214:215], v161 offset:0x2000
	ds_read_b64_tr_b16 v[216:217], v161 offset:0x2800
	ds_read_b64_tr_b16 v[218:219], v161 offset:0x3000
	ds_read_b64_tr_b16 v[220:221], v161 offset:0x3800
	s_waitcnt lgkmcnt(6)
	v_max_f32_e32 v235, v81, v81
	v_max_f32_e32 v237, v80, v80
	v_max_f32_e32 v235, v237, v235
	v_max3_f32 v235, v235, v82, v83
	v_max3_f32 v235, v235, v84, v85
	v_mfma_f32_32x32x16_bf16 v[0:15], v[194:197], v[202:205], v[0:15]
	ds_read_b64_tr_b16 v[202:203], v161 offset:0x200
	ds_read_b64_tr_b16 v[204:205], v161 offset:0xa00
	v_max3_f32 v235, v235, v86, v87
	v_max3_f32 v235, v235, v88, v89
	v_max3_f32 v235, v235, v90, v91
	v_max3_f32 v235, v235, v92, v93
	v_max3_f32 v235, v235, v94, v95
	v_max3_f32 v235, v235, v64, v65
	s_waitcnt lgkmcnt(6)
	v_mfma_f32_32x32x16_bf16 v[0:15], v[166:169], v[210:213], v[0:15]
	ds_read_b64_tr_b16 v[210:211], v161 offset:0x1200
	ds_read_b64_tr_b16 v[212:213], v161 offset:0x1a00
	v_max3_f32 v235, v235, v66, v67
	v_max3_f32 v235, v235, v68, v69
	v_max3_f32 v235, v235, v70, v71
	v_max3_f32 v235, v235, v72, v73
	v_max3_f32 v235, v235, v74, v75
	v_max3_f32 v235, v235, v76, v77
	s_waitcnt lgkmcnt(6)
	v_mfma_f32_32x32x16_bf16 v[0:15], v[162:165], v[214:217], v[0:15]
	ds_read_b64_tr_b16 v[214:215], v161 offset:0x2200
	ds_read_b64_tr_b16 v[216:217], v161 offset:0x2a00
	v_max3_f32 v235, v235, v78, v79
	v_mov_b32_e32 v237, v235
	s_waitcnt lgkmcnt(6)
	v_mfma_f32_32x32x16_bf16 v[0:15], v[198:201], v[218:221], v[0:15]
	ds_read_b64_tr_b16 v[218:219], v161 offset:0x3200
	ds_read_b64_tr_b16 v[220:221], v161 offset:0x3a00
	v_permlane32_swap_b32_e32 v235, v237
	v_max_f32_e32 v237, v237, v237
	v_max_f32_e32 v235, v235, v235
	s_waitcnt lgkmcnt(6)
	v_mfma_f32_32x32x16_bf16 v[48:63], v[194:197], v[202:205], v[48:63]
	ds_read_b64_tr_b16 v[202:203], v161 offset:0x400
	ds_read_b64_tr_b16 v[204:205], v161 offset:0xc00
	s_waitcnt lgkmcnt(6)
	v_mfma_f32_32x32x16_bf16 v[48:63], v[166:169], v[210:213], v[48:63]
	ds_read_b64_tr_b16 v[210:211], v161 offset:0x1400
	ds_read_b64_tr_b16 v[212:213], v161 offset:0x1c00
	s_waitcnt lgkmcnt(6)
	v_mfma_f32_32x32x16_bf16 v[48:63], v[162:165], v[214:217], v[48:63]
	ds_read_b64_tr_b16 v[214:215], v161 offset:0x2400
	ds_read_b64_tr_b16 v[216:217], v161 offset:0x2c00
	s_waitcnt lgkmcnt(6)
	v_mfma_f32_32x32x16_bf16 v[48:63], v[198:201], v[218:221], v[48:63]
	ds_read_b64_tr_b16 v[218:219], v161 offset:0x3400
	ds_read_b64_tr_b16 v[220:221], v161 offset:0x3c00
	s_waitcnt lgkmcnt(6)
	v_mfma_f32_32x32x16_bf16 v[32:47], v[194:197], v[202:205], v[32:47]
	ds_read_b64_tr_b16 v[202:203], v161 offset:0x600
	ds_read_b64_tr_b16 v[204:205], v161 offset:0xe00
	s_waitcnt lgkmcnt(6)
	v_mfma_f32_32x32x16_bf16 v[32:47], v[166:169], v[210:213], v[32:47]
	ds_read_b64_tr_b16 v[210:211], v161 offset:0x1600
	ds_read_b64_tr_b16 v[212:213], v161 offset:0x1e00
	s_waitcnt lgkmcnt(6)
	v_mfma_f32_32x32x16_bf16 v[32:47], v[162:165], v[214:217], v[32:47]
	ds_read_b64_tr_b16 v[214:215], v161 offset:0x2600
	ds_read_b64_tr_b16 v[216:217], v161 offset:0x2e00
	s_waitcnt lgkmcnt(6)
	v_mfma_f32_32x32x16_bf16 v[32:47], v[198:201], v[218:221], v[32:47]
	ds_read_b64_tr_b16 v[218:219], v161 offset:0x3600
	ds_read_b64_tr_b16 v[220:221], v161 offset:0x3e00
	v_max_f32_e32 v161, v235, v237
	v_sub_f32_e32 v237, v161, v160
	s_waitcnt vmcnt(0)
	s_waitcnt vmcnt(0)
	s_waitcnt lgkmcnt(0)
	s_barrier
	v_mfma_f32_32x32x16_bf16 v[16:31], v[194:197], v[202:205], v[16:31]
	v_mfma_f32_32x32x16_bf16 v[16:31], v[166:169], v[210:213], v[16:31]
	v_mfma_f32_32x32x16_bf16 v[16:31], v[162:165], v[214:217], v[16:31]
	v_mfma_f32_32x32x16_bf16 v[16:31], v[198:201], v[218:221], v[16:31]
	v_cmp_ge_f32_e32 vcc, s65, v237
	s_cmp_eq_u64 vcc, exec
	s_cselect_b64 s[38:39], -1, 0
	s_cmp_ge_u32 s12, s52
	s_cselect_b64 s[42:43], -1, 0
	s_and_b64 vcc, exec, s[42:43]
